# grid barrier: first block of an XCD to arrive also starts an L2 write-back
# baseline (speedup 1.0000x reference)
.LBB0_218:
	s_or_b64 exec, exec, s[2:3]
	v_cvt_f32_u32_e32 v4, v2
	s_waitcnt vmcnt(0)
	v_readfirstlane_b32 s2, v3
	v_sub_u32_e32 v3, 0, v2
	v_rcp_iflag_f32_e32 v4, v4
	v_add_u32_e32 v5, s2, v1
	v_mul_f32_e32 v4, 0x4f7ffffe, v4
	v_cvt_u32_f32_e32 v4, v4
	v_mul_lo_u32 v1, v3, v4
	v_mul_hi_u32 v1, v4, v1
	v_add_u32_e32 v1, v4, v1
	v_mul_hi_u32 v1, v5, v1
	v_mul_lo_u32 v3, v1, v2
	v_sub_u32_e32 v3, v5, v3
	v_add_u32_e32 v4, 1, v1
	v_cmp_ge_u32_e32 vcc, v3, v2
	s_nop 1
	v_cndmask_b32_e32 v1, v1, v4, vcc
	v_sub_u32_e32 v4, v3, v2
	v_cndmask_b32_e32 v3, v3, v4, vcc
	v_add_u32_e32 v4, 1, v1
	v_cmp_ge_u32_e32 vcc, v3, v2
	v_add_u32_e32 v3, 1, v5
	s_nop 0
	v_cndmask_b32_e32 v1, v1, v4, vcc
	v_mul_lo_u32 v4, v2, v1
	v_add_u32_e32 v2, v4, v2
	v_cmp_ne_u32_e32 vcc, v3, v2
	s_and_saveexec_b64 s[2:3], vcc
	s_xor_b64 s[2:3], exec, s[2:3]
	s_cbranch_execz .LBB0_232
	v_add_u32_e32 v10, 1, v4
	v_cmp_eq_u32_e32 vcc, v3, v10
	s_cbranch_vccz .Lgwb1
	buffer_wbl2 sc1
.Lgwb1:
	s_mov_b32 s6, s22
	s_waitcnt lgkmcnt(0)
	v_mov_b32_e32 v0, 0
	s_mov_b32 s7, s23
	s_nop 4
	global_load_dword v2, v0, s[6:7] sc1
	s_waitcnt vmcnt(0)
	v_cmp_eq_u32_e32 vcc, v2, v1
	s_and_saveexec_b64 s[6:7], vcc
	s_cbranch_execz .LBB0_231
	s_mov_b32 s19, 1
	s_mov_b64 s[8:9], 0
	s_branch .LBB0_222

.LBB0_292:
	s_or_b64 exec, exec, s[12:13]
	v_cvt_f32_u32_e32 v5, v2
	s_waitcnt vmcnt(0)
	v_readfirstlane_b32 s12, v4
	v_sub_u32_e32 v4, 0, v2
	v_rcp_iflag_f32_e32 v5, v5
	v_add_u32_e32 v6, s12, v1
	v_mul_f32_e32 v5, 0x4f7ffffe, v5
	v_cvt_u32_f32_e32 v5, v5
	v_mul_lo_u32 v1, v4, v5
	v_mul_hi_u32 v1, v5, v1
	v_add_u32_e32 v1, v5, v1
	v_mul_hi_u32 v1, v6, v1
	v_mul_lo_u32 v4, v1, v2
	v_sub_u32_e32 v4, v6, v4
	v_add_u32_e32 v5, 1, v1
	v_cmp_ge_u32_e32 vcc, v4, v2
	s_nop 1
	v_cndmask_b32_e32 v1, v1, v5, vcc
	v_sub_u32_e32 v5, v4, v2
	v_cndmask_b32_e32 v4, v4, v5, vcc
	v_add_u32_e32 v5, 1, v1
	v_cmp_ge_u32_e32 vcc, v4, v2
	v_add_u32_e32 v4, 1, v6
	s_nop 0
	v_cndmask_b32_e32 v1, v1, v5, vcc
	v_mul_lo_u32 v5, v2, v1
	v_add_u32_e32 v2, v5, v2
	v_cmp_ne_u32_e32 vcc, v4, v2
	s_and_saveexec_b64 s[12:13], vcc
	s_xor_b64 s[12:13], exec, s[12:13]
	s_cbranch_execz .LBB0_306
	v_add_u32_e32 v10, 1, v5
	v_cmp_eq_u32_e32 vcc, v4, v10
	s_cbranch_vccz .Lgwb2
	buffer_wbl2 sc1
.Lgwb2:
	v_readlane_b32 s40, v236, 36
	v_readlane_b32 s41, v236, 37
	s_waitcnt lgkmcnt(0)
	s_nop 3
	global_load_dword v0, v3, s[40:41] sc1
	s_waitcnt vmcnt(0)
	v_cmp_eq_u32_e32 vcc, v0, v1
	s_and_saveexec_b64 s[40:41], vcc
	s_cbranch_execz .LBB0_305
	s_mov_b32 s15, 1
	s_mov_b64 s[42:43], 0
	s_branch .LBB0_296

.Lgwb3:
	v_readlane_b32 s40, v236, 36
	v_readlane_b32 s41, v236, 37
	s_waitcnt lgkmcnt(0)
	s_nop 3
	global_load_dword v0, v3, s[40:41] sc1
	s_waitcnt vmcnt(0)
	v_cmp_eq_u32_e32 vcc, v0, v1
	s_and_saveexec_b64 s[40:41], vcc
	s_cbranch_execz .LBB0_512
	s_mov_b32 s34, 1
	s_mov_b64 s[42:43], 0
	s_branch .LBB0_503

.Lgwb7:
	v_readlane_b32 s4, v236, 36
	s_waitcnt lgkmcnt(0)
	v_mov_b32_e32 v0, 0
	v_readlane_b32 s5, v236, 37
	s_nop 4
	global_load_dword v2, v0, s[4:5] sc1
	s_waitcnt vmcnt(0)
	v_cmp_eq_u32_e32 vcc, v2, v1
	s_and_saveexec_b64 s[4:5], vcc
	s_cbranch_execz .LBB0_1094
	s_mov_b32 s16, 1
	s_mov_b64 s[6:7], 0
	s_branch .LBB0_1085
